# proj/gate-up K-loop load segments: LDS-DMA loads issued before the ds_read fragment reads
# speedup vs baseline: 1.0073x; 1.0016x over previous
.LBB0_342:
	s_add_u32 s33, s44, 0xfff80080
	s_addc_u32 s43, s45, -1
	s_add_i32 s50, 0, 0x10000
	s_cmp_eq_u32 s35, 28
	s_cselect_b32 s49, s27, s43
	s_cselect_b32 s48, s28, s33
	s_cselect_b32 s47, s25, s34
	s_cselect_b32 s46, s29, s31
	s_add_i32 s33, 0, 0x14000
	s_add_i32 m0, s12, 0xc000
	s_nop 0
	global_load_lds_dwordx4 v140, s[44:45]
	s_add_i32 m0, s12, 0xe000
	s_nop 0
	global_load_lds_dwordx4 v138, s[44:45]
	v_add_u32_e32 v142, s50, v149
	ds_read_b128 v[154:157], v142
	ds_read_b128 v[168:171], v142 offset:1024
	ds_read_b128 v[172:175], v142 offset:2048
	ds_read_b128 v[176:179], v142 offset:3072
	v_add_u32_e32 v142, s33, v149
	ds_read_b128 v[180:183], v142
	ds_read_b128 v[184:187], v142 offset:1024
	ds_read_b128 v[188:191], v142 offset:2048
	ds_read_b128 v[192:195], v142 offset:3072
	ds_read_b128 v[196:199], v167
	ds_read_b128 v[200:203], v167 offset:1024
	ds_read_b128 v[204:207], v167 offset:2048
	ds_read_b128 v[208:211], v167 offset:3072
	ds_read_b128 v[212:215], v167 offset:4096
	ds_read_b128 v[216:219], v167 offset:5120
	ds_read_b128 v[220:223], v167 offset:6144
	ds_read_b128 v[224:227], v167 offset:7168
	s_cmp_lg_u32 s32, 0
	s_cbranch_scc1 .Lpj_skip1
	s_waitcnt vmcnt(8)
.Lpj_skip1:
	s_waitcnt lgkmcnt(0)
	s_barrier
	s_setprio 1
	s_waitcnt lgkmcnt(0)
	v_mfma_f32_16x16x32_bf16 v[128:131], v[154:157], v[196:199], v[128:131]
	v_mfma_f32_16x16x32_bf16 v[124:127], v[172:175], v[196:199], v[124:127]
	v_mfma_f32_16x16x32_bf16 v[116:119], v[154:157], v[204:207], v[116:119]
	v_mfma_f32_16x16x32_bf16 v[108:111], v[172:175], v[204:207], v[108:111]
	v_mfma_f32_16x16x32_bf16 v[100:103], v[154:157], v[212:215], v[100:103]
	v_mfma_f32_16x16x32_bf16 v[92:95], v[172:175], v[212:215], v[92:95]
	v_mfma_f32_16x16x32_bf16 v[84:87], v[154:157], v[220:223], v[84:87]
	v_mfma_f32_16x16x32_bf16 v[76:79], v[172:175], v[220:223], v[76:79]
	v_mfma_f32_16x16x32_bf16 v[128:131], v[168:171], v[200:203], v[128:131]
	v_mfma_f32_16x16x32_bf16 v[124:127], v[176:179], v[200:203], v[124:127]
	v_mfma_f32_16x16x32_bf16 v[116:119], v[168:171], v[208:211], v[116:119]
	v_mfma_f32_16x16x32_bf16 v[108:111], v[176:179], v[208:211], v[108:111]
	v_mfma_f32_16x16x32_bf16 v[100:103], v[168:171], v[216:219], v[100:103]
	v_mfma_f32_16x16x32_bf16 v[92:95], v[176:179], v[216:219], v[92:95]
	v_mfma_f32_16x16x32_bf16 v[84:87], v[168:171], v[224:227], v[84:87]
	v_mfma_f32_16x16x32_bf16 v[76:79], v[176:179], v[224:227], v[76:79]
	v_mfma_f32_16x16x32_bf16 v[120:123], v[180:183], v[196:199], v[120:123]
	v_mfma_f32_16x16x32_bf16 v[112:115], v[188:191], v[196:199], v[112:115]
	v_mfma_f32_16x16x32_bf16 v[104:107], v[180:183], v[204:207], v[104:107]
	v_mfma_f32_16x16x32_bf16 v[96:99], v[188:191], v[204:207], v[96:99]
	v_mfma_f32_16x16x32_bf16 v[88:91], v[180:183], v[212:215], v[88:91]
	v_mfma_f32_16x16x32_bf16 v[80:83], v[188:191], v[212:215], v[80:83]
	v_mfma_f32_16x16x32_bf16 v[72:75], v[180:183], v[220:223], v[72:75]
	v_mfma_f32_16x16x32_bf16 v[68:71], v[188:191], v[220:223], v[68:71]
	v_mfma_f32_16x16x32_bf16 v[120:123], v[184:187], v[200:203], v[120:123]
	v_mfma_f32_16x16x32_bf16 v[112:115], v[192:195], v[200:203], v[112:115]
	v_mfma_f32_16x16x32_bf16 v[104:107], v[184:187], v[208:211], v[104:107]
	v_mfma_f32_16x16x32_bf16 v[96:99], v[192:195], v[208:211], v[96:99]
	v_mfma_f32_16x16x32_bf16 v[88:91], v[184:187], v[216:219], v[88:91]
	v_mfma_f32_16x16x32_bf16 v[80:83], v[192:195], v[216:219], v[80:83]
	v_mfma_f32_16x16x32_bf16 v[72:75], v[184:187], v[224:227], v[72:75]
	v_mfma_f32_16x16x32_bf16 v[68:71], v[192:195], v[224:227], v[68:71]
	s_setprio 0
	s_barrier
	s_add_i32 s43, s50, s10
	s_mov_b32 m0, s43
	s_nop 0
	global_load_lds_dwordx4 v2, s[46:47]
	s_add_i32 m0, s43, 0x2000
	s_add_u32 s50, s46, 0x80000
	s_addc_u32 s51, s47, 0
	s_add_i32 s33, s33, s10
	global_load_lds_dwordx4 v0, s[46:47]
	s_mov_b32 m0, s33
	s_nop 0
	global_load_lds_dwordx4 v2, s[50:51]
	s_add_i32 m0, s33, 0x2000
	s_nop 0
	global_load_lds_dwordx4 v0, s[50:51]
	s_mov_b32 m0, s12
	s_nop 0
	global_load_lds_dwordx4 v134, s[48:49]
	s_mov_b32 m0, s13
	s_nop 0
	global_load_lds_dwordx4 v132, s[48:49]
	ds_read_b128 v[196:199], v167 offset:16384
	ds_read_b128 v[200:203], v167 offset:17408
	ds_read_b128 v[204:207], v167 offset:18432
	ds_read_b128 v[208:211], v167 offset:19456
	ds_read_b128 v[212:215], v167 offset:20480
	ds_read_b128 v[216:219], v167 offset:21504
	ds_read_b128 v[220:223], v167 offset:22528
	ds_read_b128 v[224:227], v167 offset:23552
	s_cmp_lg_u32 s32, 0
	s_cbranch_scc1 .Lpj_skip2
	s_waitcnt vmcnt(8)
.Lpj_skip2:
	s_mov_b32 s32, 0
	s_waitcnt lgkmcnt(0)
	s_barrier
	s_setprio 1
	s_waitcnt lgkmcnt(0)
	v_mfma_f32_16x16x32_bf16 v[64:67], v[154:157], v[196:199], v[64:67]
	v_mfma_f32_16x16x32_bf16 v[60:63], v[172:175], v[196:199], v[60:63]
	v_mfma_f32_16x16x32_bf16 v[52:55], v[154:157], v[204:207], v[52:55]
	v_mfma_f32_16x16x32_bf16 v[44:47], v[172:175], v[204:207], v[44:47]
	v_mfma_f32_16x16x32_bf16 v[36:39], v[154:157], v[212:215], v[36:39]
	v_mfma_f32_16x16x32_bf16 v[28:31], v[172:175], v[212:215], v[28:31]
	v_mfma_f32_16x16x32_bf16 v[20:23], v[154:157], v[220:223], v[20:23]
	v_mfma_f32_16x16x32_bf16 v[12:15], v[172:175], v[220:223], v[12:15]
	v_mfma_f32_16x16x32_bf16 v[64:67], v[168:171], v[200:203], v[64:67]
	v_mfma_f32_16x16x32_bf16 v[60:63], v[176:179], v[200:203], v[60:63]
	v_mfma_f32_16x16x32_bf16 v[52:55], v[168:171], v[208:211], v[52:55]
	v_mfma_f32_16x16x32_bf16 v[44:47], v[176:179], v[208:211], v[44:47]
	v_mfma_f32_16x16x32_bf16 v[36:39], v[168:171], v[216:219], v[36:39]
	v_mfma_f32_16x16x32_bf16 v[28:31], v[176:179], v[216:219], v[28:31]
	v_mfma_f32_16x16x32_bf16 v[20:23], v[168:171], v[224:227], v[20:23]
	v_mfma_f32_16x16x32_bf16 v[12:15], v[176:179], v[224:227], v[12:15]
	v_mfma_f32_16x16x32_bf16 v[56:59], v[180:183], v[196:199], v[56:59]
	v_mfma_f32_16x16x32_bf16 v[48:51], v[188:191], v[196:199], v[48:51]
	v_mfma_f32_16x16x32_bf16 v[40:43], v[180:183], v[204:207], v[40:43]
	v_mfma_f32_16x16x32_bf16 v[32:35], v[188:191], v[204:207], v[32:35]
	v_mfma_f32_16x16x32_bf16 v[24:27], v[180:183], v[212:215], v[24:27]
	v_mfma_f32_16x16x32_bf16 v[16:19], v[188:191], v[212:215], v[16:19]
	v_mfma_f32_16x16x32_bf16 v[8:11], v[180:183], v[220:223], v[8:11]
	v_mfma_f32_16x16x32_bf16 v[4:7], v[188:191], v[220:223], v[4:7]
	v_mfma_f32_16x16x32_bf16 v[56:59], v[184:187], v[200:203], v[56:59]
	v_mfma_f32_16x16x32_bf16 v[48:51], v[192:195], v[200:203], v[48:51]
	v_mfma_f32_16x16x32_bf16 v[40:43], v[184:187], v[208:211], v[40:43]
	v_mfma_f32_16x16x32_bf16 v[32:35], v[192:195], v[208:211], v[32:35]
	v_mfma_f32_16x16x32_bf16 v[24:27], v[184:187], v[216:219], v[24:27]
	v_mfma_f32_16x16x32_bf16 v[16:19], v[192:195], v[216:219], v[16:19]
	v_mfma_f32_16x16x32_bf16 v[8:11], v[184:187], v[224:227], v[8:11]
	v_mfma_f32_16x16x32_bf16 v[4:7], v[192:195], v[224:227], v[4:7]
	s_setprio 0
	s_barrier
	s_add_i32 s33, 0, 0x18000
	s_add_i32 s43, 0, 0x1c000
	s_add_u32 s48, s48, 0x80000
	s_addc_u32 s49, s49, 0
	s_mov_b32 m0, s14
	s_nop 0
	global_load_lds_dwordx4 v134, s[48:49]
	s_mov_b32 m0, s15
	s_nop 0
	global_load_lds_dwordx4 v132, s[48:49]
	v_add_u32_e32 v144, s33, v149
	ds_read_b128 v[154:157], v144
	ds_read_b128 v[168:171], v144 offset:1024
	ds_read_b128 v[172:175], v144 offset:2048
	ds_read_b128 v[176:179], v144 offset:3072
	v_add_u32_e32 v144, s43, v149
	ds_read_b128 v[180:183], v144
	ds_read_b128 v[184:187], v144 offset:1024
	ds_read_b128 v[188:191], v144 offset:2048
	ds_read_b128 v[192:195], v144 offset:3072
	ds_read_b128 v[196:199], v167 offset:32768
	ds_read_b128 v[200:203], v167 offset:33792
	ds_read_b128 v[204:207], v167 offset:34816
	ds_read_b128 v[208:211], v167 offset:35840
	ds_read_b128 v[212:215], v167 offset:36864
	ds_read_b128 v[216:219], v167 offset:37888
	ds_read_b128 v[220:223], v167 offset:38912
	ds_read_b128 v[224:227], v167 offset:39936
	s_waitcnt vmcnt(8)
	s_waitcnt lgkmcnt(0)
	s_barrier
	s_setprio 1
	s_waitcnt lgkmcnt(0)
	v_mfma_f32_16x16x32_bf16 v[128:131], v[154:157], v[196:199], v[128:131]
	v_mfma_f32_16x16x32_bf16 v[124:127], v[172:175], v[196:199], v[124:127]
	v_mfma_f32_16x16x32_bf16 v[116:119], v[154:157], v[204:207], v[116:119]
	v_mfma_f32_16x16x32_bf16 v[108:111], v[172:175], v[204:207], v[108:111]
	v_mfma_f32_16x16x32_bf16 v[100:103], v[154:157], v[212:215], v[100:103]
	v_mfma_f32_16x16x32_bf16 v[92:95], v[172:175], v[212:215], v[92:95]
	v_mfma_f32_16x16x32_bf16 v[84:87], v[154:157], v[220:223], v[84:87]
	v_mfma_f32_16x16x32_bf16 v[76:79], v[172:175], v[220:223], v[76:79]
	v_mfma_f32_16x16x32_bf16 v[128:131], v[168:171], v[200:203], v[128:131]
	v_mfma_f32_16x16x32_bf16 v[124:127], v[176:179], v[200:203], v[124:127]
	v_mfma_f32_16x16x32_bf16 v[116:119], v[168:171], v[208:211], v[116:119]
	v_mfma_f32_16x16x32_bf16 v[108:111], v[176:179], v[208:211], v[108:111]
	v_mfma_f32_16x16x32_bf16 v[100:103], v[168:171], v[216:219], v[100:103]
	v_mfma_f32_16x16x32_bf16 v[92:95], v[176:179], v[216:219], v[92:95]
	v_mfma_f32_16x16x32_bf16 v[84:87], v[168:171], v[224:227], v[84:87]
	v_mfma_f32_16x16x32_bf16 v[76:79], v[176:179], v[224:227], v[76:79]
	v_mfma_f32_16x16x32_bf16 v[120:123], v[180:183], v[196:199], v[120:123]
	v_mfma_f32_16x16x32_bf16 v[112:115], v[188:191], v[196:199], v[112:115]
	v_mfma_f32_16x16x32_bf16 v[104:107], v[180:183], v[204:207], v[104:107]
	v_mfma_f32_16x16x32_bf16 v[96:99], v[188:191], v[204:207], v[96:99]
	v_mfma_f32_16x16x32_bf16 v[88:91], v[180:183], v[212:215], v[88:91]
	v_mfma_f32_16x16x32_bf16 v[80:83], v[188:191], v[212:215], v[80:83]
	v_mfma_f32_16x16x32_bf16 v[72:75], v[180:183], v[220:223], v[72:75]
	v_mfma_f32_16x16x32_bf16 v[68:71], v[188:191], v[220:223], v[68:71]
	v_mfma_f32_16x16x32_bf16 v[120:123], v[184:187], v[200:203], v[120:123]
	v_mfma_f32_16x16x32_bf16 v[112:115], v[192:195], v[200:203], v[112:115]
	v_mfma_f32_16x16x32_bf16 v[104:107], v[184:187], v[208:211], v[104:107]
	v_mfma_f32_16x16x32_bf16 v[96:99], v[192:195], v[208:211], v[96:99]
	v_mfma_f32_16x16x32_bf16 v[88:91], v[184:187], v[216:219], v[88:91]
	v_mfma_f32_16x16x32_bf16 v[80:83], v[192:195], v[216:219], v[80:83]
	v_mfma_f32_16x16x32_bf16 v[72:75], v[184:187], v[224:227], v[72:75]
	v_mfma_f32_16x16x32_bf16 v[68:71], v[192:195], v[224:227], v[68:71]
	s_setprio 0
	s_barrier
	s_add_i32 s33, s33, s10
	s_mov_b32 m0, s33
	s_add_u32 s100, s46, 0x80
	s_addc_u32 s101, s47, 0
	global_load_lds_dwordx4 v2, s[100:101]
	s_add_i32 m0, s33, 0x2000
	s_add_u32 s46, s46, 0x80080
	s_addc_u32 s47, s47, 0
	s_add_i32 s33, s43, s10
	s_add_u32 s100, s46, 0xfff80000
	s_addc_u32 s101, s47, -1
	global_load_lds_dwordx4 v0, s[100:101]
	s_mov_b32 m0, s33
	s_nop 0
	global_load_lds_dwordx4 v2, s[46:47]
	s_add_i32 m0, s33, 0x2000
	s_nop 0
	global_load_lds_dwordx4 v0, s[46:47]
	s_mov_b32 m0, s16
	s_nop 0
	s_add_u32 s100, s48, 0xfff80080
	s_addc_u32 s101, s49, -1
	global_load_lds_dwordx4 v134, s[100:101]
	s_mov_b32 m0, s17
	s_nop 0
	s_add_u32 s100, s48, 0xfff80080
	s_addc_u32 s101, s49, -1
	global_load_lds_dwordx4 v132, s[100:101]
	ds_read_b128 v[196:199], v167 offset:49152
	ds_read_b128 v[200:203], v167 offset:50176
	ds_read_b128 v[204:207], v167 offset:51200
	ds_read_b128 v[208:211], v167 offset:52224
	ds_read_b128 v[212:215], v167 offset:53248
	ds_read_b128 v[216:219], v167 offset:54272
	ds_read_b128 v[220:223], v167 offset:55296
	ds_read_b128 v[224:227], v167 offset:56320
	s_waitcnt vmcnt(8)
	s_waitcnt lgkmcnt(0)
	s_barrier
	s_setprio 1
	s_waitcnt lgkmcnt(0)
	v_mfma_f32_16x16x32_bf16 v[64:67], v[154:157], v[196:199], v[64:67]
	v_mfma_f32_16x16x32_bf16 v[60:63], v[172:175], v[196:199], v[60:63]
	v_mfma_f32_16x16x32_bf16 v[52:55], v[154:157], v[204:207], v[52:55]
	v_mfma_f32_16x16x32_bf16 v[44:47], v[172:175], v[204:207], v[44:47]
	v_mfma_f32_16x16x32_bf16 v[36:39], v[154:157], v[212:215], v[36:39]
	v_mfma_f32_16x16x32_bf16 v[28:31], v[172:175], v[212:215], v[28:31]
	v_mfma_f32_16x16x32_bf16 v[20:23], v[154:157], v[220:223], v[20:23]
	v_mfma_f32_16x16x32_bf16 v[12:15], v[172:175], v[220:223], v[12:15]
	v_mfma_f32_16x16x32_bf16 v[64:67], v[168:171], v[200:203], v[64:67]
	v_mfma_f32_16x16x32_bf16 v[60:63], v[176:179], v[200:203], v[60:63]
	v_mfma_f32_16x16x32_bf16 v[52:55], v[168:171], v[208:211], v[52:55]
	v_mfma_f32_16x16x32_bf16 v[44:47], v[176:179], v[208:211], v[44:47]
	v_mfma_f32_16x16x32_bf16 v[36:39], v[168:171], v[216:219], v[36:39]
	v_mfma_f32_16x16x32_bf16 v[28:31], v[176:179], v[216:219], v[28:31]
	v_mfma_f32_16x16x32_bf16 v[20:23], v[168:171], v[224:227], v[20:23]
	v_mfma_f32_16x16x32_bf16 v[12:15], v[176:179], v[224:227], v[12:15]
	v_mfma_f32_16x16x32_bf16 v[56:59], v[180:183], v[196:199], v[56:59]
	v_mfma_f32_16x16x32_bf16 v[48:51], v[188:191], v[196:199], v[48:51]
	v_mfma_f32_16x16x32_bf16 v[40:43], v[180:183], v[204:207], v[40:43]
	v_mfma_f32_16x16x32_bf16 v[32:35], v[188:191], v[204:207], v[32:35]
	v_mfma_f32_16x16x32_bf16 v[24:27], v[180:183], v[212:215], v[24:27]
	v_mfma_f32_16x16x32_bf16 v[16:19], v[188:191], v[212:215], v[16:19]
	v_mfma_f32_16x16x32_bf16 v[8:11], v[180:183], v[220:223], v[8:11]
	v_mfma_f32_16x16x32_bf16 v[4:7], v[188:191], v[220:223], v[4:7]
	v_mfma_f32_16x16x32_bf16 v[56:59], v[184:187], v[200:203], v[56:59]
	v_mfma_f32_16x16x32_bf16 v[48:51], v[192:195], v[200:203], v[48:51]
	v_mfma_f32_16x16x32_bf16 v[40:43], v[184:187], v[208:211], v[40:43]
	v_mfma_f32_16x16x32_bf16 v[32:35], v[192:195], v[208:211], v[32:35]
	v_mfma_f32_16x16x32_bf16 v[24:27], v[184:187], v[216:219], v[24:27]
	v_mfma_f32_16x16x32_bf16 v[16:19], v[192:195], v[216:219], v[16:19]
	v_mfma_f32_16x16x32_bf16 v[8:11], v[184:187], v[224:227], v[8:11]
	v_mfma_f32_16x16x32_bf16 v[4:7], v[192:195], v[224:227], v[4:7]
	s_setprio 0
	s_barrier
	s_add_i32 s35, s35, 2
	s_add_u32 s31, s31, 0x100
	s_addc_u32 s34, s34, 0
	s_add_u32 s44, s44, 0x100
	s_addc_u32 s45, s45, 0
	s_cmp_gt_u32 s35, 29
	s_cbranch_scc0 .LBB0_342
	s_and_b64 vcc, exec, s[22:23]
	s_cbranch_vccz .LBB0_345
	s_barrier

.LBB0_1066:
	s_add_u32 s12, s44, 0xfff80080
	s_addc_u32 s13, s45, -1
	s_add_i32 s14, 0, 0x10000
	s_cmp_eq_u32 s11, 28
	s_cselect_b32 s49, s5, s13
	s_cselect_b32 s48, s6, s12
	s_cselect_b32 s47, s7, s10
	s_cselect_b32 s46, s8, s9
	s_add_i32 s15, 0, 0x14000
	s_add_i32 m0, s60, 0xc000
	s_nop 0
	global_load_lds_dwordx4 v140, s[44:45]
	s_add_i32 m0, s60, 0xe000
	s_nop 0
	global_load_lds_dwordx4 v138, s[44:45]
	v_add_u32_e32 v154, s14, v163
	v_add_u32_e32 v158, s15, v163
	ds_read_b128 v[142:145], v154
	ds_read_b128 v[146:149], v154 offset:1024
	ds_read_b128 v[150:153], v154 offset:2048
	ds_read_b128 v[154:157], v154 offset:3072
	ds_read_b128 v[168:171], v158
	ds_read_b128 v[172:175], v158 offset:1024
	ds_read_b128 v[176:179], v158 offset:2048
	ds_read_b128 v[180:183], v158 offset:3072
	ds_read_b128 v[184:187], v167
	ds_read_b128 v[188:191], v167 offset:1024
	ds_read_b128 v[192:195], v167 offset:2048
	ds_read_b128 v[196:199], v167 offset:3072
	ds_read_b128 v[200:203], v167 offset:4096
	ds_read_b128 v[204:207], v167 offset:5120
	ds_read_b128 v[208:211], v167 offset:6144
	ds_read_b128 v[212:215], v167 offset:7168
	s_cmp_lg_u32 s32, 0
	s_cbranch_scc1 .Lgu_skip1
	s_waitcnt vmcnt(8)
.Lgu_skip1:
	s_waitcnt lgkmcnt(0)
	s_barrier
	s_setprio 1
	s_waitcnt lgkmcnt(0)
	v_mfma_f32_16x16x32_bf16 v[124:127], v[142:145], v[184:187], v[124:127]
	v_mfma_f32_16x16x32_bf16 v[120:123], v[150:153], v[184:187], v[120:123]
	v_mfma_f32_16x16x32_bf16 v[112:115], v[142:145], v[192:195], v[112:115]
	v_mfma_f32_16x16x32_bf16 v[104:107], v[150:153], v[192:195], v[104:107]
	v_mfma_f32_16x16x32_bf16 v[96:99], v[142:145], v[200:203], v[96:99]
	v_mfma_f32_16x16x32_bf16 v[88:91], v[150:153], v[200:203], v[88:91]
	v_mfma_f32_16x16x32_bf16 v[80:83], v[142:145], v[208:211], v[80:83]
	v_mfma_f32_16x16x32_bf16 v[72:75], v[150:153], v[208:211], v[72:75]
	v_mfma_f32_16x16x32_bf16 v[124:127], v[146:149], v[188:191], v[124:127]
	v_mfma_f32_16x16x32_bf16 v[120:123], v[154:157], v[188:191], v[120:123]
	v_mfma_f32_16x16x32_bf16 v[112:115], v[146:149], v[196:199], v[112:115]
	v_mfma_f32_16x16x32_bf16 v[104:107], v[154:157], v[196:199], v[104:107]
	v_mfma_f32_16x16x32_bf16 v[96:99], v[146:149], v[204:207], v[96:99]
	v_mfma_f32_16x16x32_bf16 v[88:91], v[154:157], v[204:207], v[88:91]
	v_mfma_f32_16x16x32_bf16 v[80:83], v[146:149], v[212:215], v[80:83]
	v_mfma_f32_16x16x32_bf16 v[72:75], v[154:157], v[212:215], v[72:75]
	v_mfma_f32_16x16x32_bf16 v[128:131], v[168:171], v[184:187], v[128:131]
	v_mfma_f32_16x16x32_bf16 v[116:119], v[176:179], v[184:187], v[116:119]
	v_mfma_f32_16x16x32_bf16 v[108:111], v[168:171], v[192:195], v[108:111]
	v_mfma_f32_16x16x32_bf16 v[100:103], v[176:179], v[192:195], v[100:103]
	v_mfma_f32_16x16x32_bf16 v[92:95], v[168:171], v[200:203], v[92:95]
	v_mfma_f32_16x16x32_bf16 v[84:87], v[176:179], v[200:203], v[84:87]
	v_mfma_f32_16x16x32_bf16 v[76:79], v[168:171], v[208:211], v[76:79]
	v_mfma_f32_16x16x32_bf16 v[68:71], v[176:179], v[208:211], v[68:71]
	v_mfma_f32_16x16x32_bf16 v[128:131], v[172:175], v[188:191], v[128:131]
	v_mfma_f32_16x16x32_bf16 v[116:119], v[180:183], v[188:191], v[116:119]
	v_mfma_f32_16x16x32_bf16 v[108:111], v[172:175], v[196:199], v[108:111]
	v_mfma_f32_16x16x32_bf16 v[100:103], v[180:183], v[196:199], v[100:103]
	v_mfma_f32_16x16x32_bf16 v[92:95], v[172:175], v[204:207], v[92:95]
	v_mfma_f32_16x16x32_bf16 v[84:87], v[180:183], v[204:207], v[84:87]
	v_mfma_f32_16x16x32_bf16 v[76:79], v[172:175], v[212:215], v[76:79]
	v_mfma_f32_16x16x32_bf16 v[68:71], v[180:183], v[212:215], v[68:71]
	s_setprio 0
	s_barrier
	s_add_i32 s12, s14, s56
	s_mov_b32 m0, s12
	s_nop 0
	global_load_lds_dwordx4 v2, s[46:47]
	s_add_i32 m0, s12, 0x2000
	s_add_u32 s12, s46, 0x80000
	s_addc_u32 s13, s47, 0
	s_add_i32 s14, s15, s56
	global_load_lds_dwordx4 v0, s[46:47]
	s_mov_b32 m0, s14
	s_nop 0
	global_load_lds_dwordx4 v2, s[12:13]
	s_add_i32 m0, s14, 0x2000
	s_nop 0
	global_load_lds_dwordx4 v0, s[12:13]
	s_mov_b32 m0, s60
	s_nop 0
	global_load_lds_dwordx4 v134, s[48:49]
	s_mov_b32 m0, s61
	s_nop 0
	global_load_lds_dwordx4 v132, s[48:49]
	ds_read_b128 v[184:187], v167 offset:16384
	ds_read_b128 v[188:191], v167 offset:17408
	ds_read_b128 v[192:195], v167 offset:18432
	ds_read_b128 v[196:199], v167 offset:19456
	ds_read_b128 v[200:203], v167 offset:20480
	ds_read_b128 v[204:207], v167 offset:21504
	ds_read_b128 v[208:211], v167 offset:22528
	ds_read_b128 v[212:215], v167 offset:23552
	s_cmp_lg_u32 s32, 0
	s_cbranch_scc1 .Lgu_skip2
	s_waitcnt vmcnt(8)
.Lgu_skip2:
	s_mov_b32 s32, 0
	s_waitcnt lgkmcnt(0)
	s_barrier
	s_setprio 1
	s_waitcnt lgkmcnt(0)
	v_mfma_f32_16x16x32_bf16 v[64:67], v[142:145], v[184:187], v[64:67]
	v_mfma_f32_16x16x32_bf16 v[56:59], v[150:153], v[184:187], v[56:59]
	v_mfma_f32_16x16x32_bf16 v[48:51], v[142:145], v[192:195], v[48:51]
	v_mfma_f32_16x16x32_bf16 v[40:43], v[150:153], v[192:195], v[40:43]
	v_mfma_f32_16x16x32_bf16 v[32:35], v[142:145], v[200:203], v[32:35]
	v_mfma_f32_16x16x32_bf16 v[24:27], v[150:153], v[200:203], v[24:27]
	v_mfma_f32_16x16x32_bf16 v[16:19], v[142:145], v[208:211], v[16:19]
	v_mfma_f32_16x16x32_bf16 v[8:11], v[150:153], v[208:211], v[8:11]
	v_mfma_f32_16x16x32_bf16 v[64:67], v[146:149], v[188:191], v[64:67]
	v_mfma_f32_16x16x32_bf16 v[56:59], v[154:157], v[188:191], v[56:59]
	v_mfma_f32_16x16x32_bf16 v[48:51], v[146:149], v[196:199], v[48:51]
	v_mfma_f32_16x16x32_bf16 v[40:43], v[154:157], v[196:199], v[40:43]
	v_mfma_f32_16x16x32_bf16 v[32:35], v[146:149], v[204:207], v[32:35]
	v_mfma_f32_16x16x32_bf16 v[24:27], v[154:157], v[204:207], v[24:27]
	v_mfma_f32_16x16x32_bf16 v[16:19], v[146:149], v[212:215], v[16:19]
	v_mfma_f32_16x16x32_bf16 v[8:11], v[154:157], v[212:215], v[8:11]
	v_mfma_f32_16x16x32_bf16 v[60:63], v[168:171], v[184:187], v[60:63]
	v_mfma_f32_16x16x32_bf16 v[52:55], v[176:179], v[184:187], v[52:55]
	v_mfma_f32_16x16x32_bf16 v[44:47], v[168:171], v[192:195], v[44:47]
	v_mfma_f32_16x16x32_bf16 v[36:39], v[176:179], v[192:195], v[36:39]
	v_mfma_f32_16x16x32_bf16 v[28:31], v[168:171], v[200:203], v[28:31]
	v_mfma_f32_16x16x32_bf16 v[20:23], v[176:179], v[200:203], v[20:23]
	v_mfma_f32_16x16x32_bf16 v[12:15], v[168:171], v[208:211], v[12:15]
	v_mfma_f32_16x16x32_bf16 v[4:7], v[176:179], v[208:211], v[4:7]
	v_mfma_f32_16x16x32_bf16 v[60:63], v[172:175], v[188:191], v[60:63]
	v_mfma_f32_16x16x32_bf16 v[52:55], v[180:183], v[188:191], v[52:55]
	v_mfma_f32_16x16x32_bf16 v[44:47], v[172:175], v[196:199], v[44:47]
	v_mfma_f32_16x16x32_bf16 v[36:39], v[180:183], v[196:199], v[36:39]
	v_mfma_f32_16x16x32_bf16 v[28:31], v[172:175], v[204:207], v[28:31]
	v_mfma_f32_16x16x32_bf16 v[20:23], v[180:183], v[204:207], v[20:23]
	v_mfma_f32_16x16x32_bf16 v[12:15], v[172:175], v[212:215], v[12:15]
	v_mfma_f32_16x16x32_bf16 v[4:7], v[180:183], v[212:215], v[4:7]
	s_setprio 0
	s_barrier
	s_add_i32 s14, 0, 0x18000
	s_add_i32 s15, 0, 0x1c000
	s_add_u32 s12, s48, 0x80000
	s_addc_u32 s13, s49, 0
	s_mov_b32 m0, s62
	s_nop 0
	global_load_lds_dwordx4 v134, s[12:13]
	s_mov_b32 m0, s63
	s_nop 0
	global_load_lds_dwordx4 v132, s[12:13]
	v_add_u32_e32 v154, s14, v163
	v_add_u32_e32 v160, s15, v163
	ds_read_b128 v[142:145], v154
	ds_read_b128 v[146:149], v154 offset:1024
	ds_read_b128 v[150:153], v154 offset:2048
	ds_read_b128 v[154:157], v154 offset:3072
	ds_read_b128 v[168:171], v160
	ds_read_b128 v[172:175], v160 offset:1024
	ds_read_b128 v[176:179], v160 offset:2048
	ds_read_b128 v[180:183], v160 offset:3072
	ds_read_b128 v[184:187], v167 offset:32768
	ds_read_b128 v[188:191], v167 offset:33792
	ds_read_b128 v[192:195], v167 offset:34816
	ds_read_b128 v[196:199], v167 offset:35840
	ds_read_b128 v[200:203], v167 offset:36864
	ds_read_b128 v[204:207], v167 offset:37888
	ds_read_b128 v[208:211], v167 offset:38912
	ds_read_b128 v[212:215], v167 offset:39936
	s_waitcnt vmcnt(8)
	s_waitcnt lgkmcnt(0)
	s_barrier
	s_setprio 1
	s_waitcnt lgkmcnt(0)
	v_mfma_f32_16x16x32_bf16 v[124:127], v[142:145], v[184:187], v[124:127]
	v_mfma_f32_16x16x32_bf16 v[120:123], v[150:153], v[184:187], v[120:123]
	v_mfma_f32_16x16x32_bf16 v[112:115], v[142:145], v[192:195], v[112:115]
	v_mfma_f32_16x16x32_bf16 v[104:107], v[150:153], v[192:195], v[104:107]
	v_mfma_f32_16x16x32_bf16 v[96:99], v[142:145], v[200:203], v[96:99]
	v_mfma_f32_16x16x32_bf16 v[88:91], v[150:153], v[200:203], v[88:91]
	v_mfma_f32_16x16x32_bf16 v[80:83], v[142:145], v[208:211], v[80:83]
	v_mfma_f32_16x16x32_bf16 v[72:75], v[150:153], v[208:211], v[72:75]
	v_mfma_f32_16x16x32_bf16 v[124:127], v[146:149], v[188:191], v[124:127]
	v_mfma_f32_16x16x32_bf16 v[120:123], v[154:157], v[188:191], v[120:123]
	v_mfma_f32_16x16x32_bf16 v[112:115], v[146:149], v[196:199], v[112:115]
	v_mfma_f32_16x16x32_bf16 v[104:107], v[154:157], v[196:199], v[104:107]
	v_mfma_f32_16x16x32_bf16 v[96:99], v[146:149], v[204:207], v[96:99]
	v_mfma_f32_16x16x32_bf16 v[88:91], v[154:157], v[204:207], v[88:91]
	v_mfma_f32_16x16x32_bf16 v[80:83], v[146:149], v[212:215], v[80:83]
	v_mfma_f32_16x16x32_bf16 v[72:75], v[154:157], v[212:215], v[72:75]
	v_mfma_f32_16x16x32_bf16 v[128:131], v[168:171], v[184:187], v[128:131]
	v_mfma_f32_16x16x32_bf16 v[116:119], v[176:179], v[184:187], v[116:119]
	v_mfma_f32_16x16x32_bf16 v[108:111], v[168:171], v[192:195], v[108:111]
	v_mfma_f32_16x16x32_bf16 v[100:103], v[176:179], v[192:195], v[100:103]
	v_mfma_f32_16x16x32_bf16 v[92:95], v[168:171], v[200:203], v[92:95]
	v_mfma_f32_16x16x32_bf16 v[84:87], v[176:179], v[200:203], v[84:87]
	v_mfma_f32_16x16x32_bf16 v[76:79], v[168:171], v[208:211], v[76:79]
	v_mfma_f32_16x16x32_bf16 v[68:71], v[176:179], v[208:211], v[68:71]
	v_mfma_f32_16x16x32_bf16 v[128:131], v[172:175], v[188:191], v[128:131]
	v_mfma_f32_16x16x32_bf16 v[116:119], v[180:183], v[188:191], v[116:119]
	v_mfma_f32_16x16x32_bf16 v[108:111], v[172:175], v[196:199], v[108:111]
	v_mfma_f32_16x16x32_bf16 v[100:103], v[180:183], v[196:199], v[100:103]
	v_mfma_f32_16x16x32_bf16 v[92:95], v[172:175], v[204:207], v[92:95]
	v_mfma_f32_16x16x32_bf16 v[84:87], v[180:183], v[204:207], v[84:87]
	v_mfma_f32_16x16x32_bf16 v[76:79], v[172:175], v[212:215], v[76:79]
	v_mfma_f32_16x16x32_bf16 v[68:71], v[180:183], v[212:215], v[68:71]
	s_setprio 0
	s_barrier
	s_add_i32 s12, s14, s56
	s_mov_b32 m0, s12
	s_add_u32 s100, s46, 0x80
	s_addc_u32 s101, s47, 0
	global_load_lds_dwordx4 v2, s[100:101]
	s_add_i32 m0, s12, 0x2000
	s_add_u32 s12, s46, 0x80080
	s_addc_u32 s13, s47, 0
	s_add_i32 s14, s15, s56
	s_add_u32 s100, s46, 0x80
	s_addc_u32 s101, s47, 0
	global_load_lds_dwordx4 v0, s[100:101]
	s_mov_b32 m0, s14
	s_nop 0
	global_load_lds_dwordx4 v2, s[12:13]
	s_add_i32 m0, s14, 0x2000
	s_nop 0
	global_load_lds_dwordx4 v0, s[12:13]
	s_mov_b32 m0, s64
	s_nop 0
	s_add_u32 s100, s48, 0x80
	s_addc_u32 s101, s49, 0
	global_load_lds_dwordx4 v134, s[100:101]
	s_mov_b32 m0, s65
	s_nop 0
	s_add_u32 s100, s48, 0x80
	s_addc_u32 s101, s49, 0
	global_load_lds_dwordx4 v132, s[100:101]
	ds_read_b128 v[184:187], v167 offset:49152
	ds_read_b128 v[188:191], v167 offset:50176
	ds_read_b128 v[192:195], v167 offset:51200
	ds_read_b128 v[196:199], v167 offset:52224
	ds_read_b128 v[200:203], v167 offset:53248
	ds_read_b128 v[204:207], v167 offset:54272
	ds_read_b128 v[208:211], v167 offset:55296
	ds_read_b128 v[212:215], v167 offset:56320
	s_waitcnt vmcnt(8)
	s_waitcnt lgkmcnt(0)
	s_barrier
	s_setprio 1
	s_waitcnt lgkmcnt(0)
	v_mfma_f32_16x16x32_bf16 v[64:67], v[142:145], v[184:187], v[64:67]
	v_mfma_f32_16x16x32_bf16 v[56:59], v[150:153], v[184:187], v[56:59]
	v_mfma_f32_16x16x32_bf16 v[48:51], v[142:145], v[192:195], v[48:51]
	v_mfma_f32_16x16x32_bf16 v[40:43], v[150:153], v[192:195], v[40:43]
	v_mfma_f32_16x16x32_bf16 v[32:35], v[142:145], v[200:203], v[32:35]
	v_mfma_f32_16x16x32_bf16 v[24:27], v[150:153], v[200:203], v[24:27]
	v_mfma_f32_16x16x32_bf16 v[16:19], v[142:145], v[208:211], v[16:19]
	v_mfma_f32_16x16x32_bf16 v[8:11], v[150:153], v[208:211], v[8:11]
	v_mfma_f32_16x16x32_bf16 v[64:67], v[146:149], v[188:191], v[64:67]
	v_mfma_f32_16x16x32_bf16 v[56:59], v[154:157], v[188:191], v[56:59]
	v_mfma_f32_16x16x32_bf16 v[48:51], v[146:149], v[196:199], v[48:51]
	v_mfma_f32_16x16x32_bf16 v[40:43], v[154:157], v[196:199], v[40:43]
	v_mfma_f32_16x16x32_bf16 v[32:35], v[146:149], v[204:207], v[32:35]
	v_mfma_f32_16x16x32_bf16 v[24:27], v[154:157], v[204:207], v[24:27]
	v_mfma_f32_16x16x32_bf16 v[16:19], v[146:149], v[212:215], v[16:19]
	v_mfma_f32_16x16x32_bf16 v[8:11], v[154:157], v[212:215], v[8:11]
	v_mfma_f32_16x16x32_bf16 v[60:63], v[168:171], v[184:187], v[60:63]
	v_mfma_f32_16x16x32_bf16 v[52:55], v[176:179], v[184:187], v[52:55]
	v_mfma_f32_16x16x32_bf16 v[44:47], v[168:171], v[192:195], v[44:47]
	v_mfma_f32_16x16x32_bf16 v[36:39], v[176:179], v[192:195], v[36:39]
	v_mfma_f32_16x16x32_bf16 v[28:31], v[168:171], v[200:203], v[28:31]
	v_mfma_f32_16x16x32_bf16 v[20:23], v[176:179], v[200:203], v[20:23]
	v_mfma_f32_16x16x32_bf16 v[12:15], v[168:171], v[208:211], v[12:15]
	v_mfma_f32_16x16x32_bf16 v[4:7], v[176:179], v[208:211], v[4:7]
	v_mfma_f32_16x16x32_bf16 v[60:63], v[172:175], v[188:191], v[60:63]
	v_mfma_f32_16x16x32_bf16 v[52:55], v[180:183], v[188:191], v[52:55]
	v_mfma_f32_16x16x32_bf16 v[44:47], v[172:175], v[196:199], v[44:47]
	v_mfma_f32_16x16x32_bf16 v[36:39], v[180:183], v[196:199], v[36:39]
	v_mfma_f32_16x16x32_bf16 v[28:31], v[172:175], v[204:207], v[28:31]
	v_mfma_f32_16x16x32_bf16 v[20:23], v[180:183], v[204:207], v[20:23]
	v_mfma_f32_16x16x32_bf16 v[12:15], v[172:175], v[212:215], v[12:15]
	v_mfma_f32_16x16x32_bf16 v[4:7], v[180:183], v[212:215], v[4:7]
	s_setprio 0
	s_barrier
	s_add_i32 s11, s11, 2
	s_add_u32 s9, s9, 0x100
	s_addc_u32 s10, s10, 0
	s_add_u32 s44, s44, 0x100
	s_addc_u32 s45, s45, 0
	s_cmp_gt_u32 s11, 29
	s_cbranch_scc0 .LBB0_1066
	s_and_b64 vcc, exec, s[22:23]
	s_cbranch_vccz .LBB0_1069
	s_barrier
